# mod_task GEMV: weight loads issued one iteration (32 loads) ahead into a second register set
# speedup vs baseline: 1.1425x; 1.0144x over previous
.LBB0_54:
	s_or_b64 exec, exec, s[0:1]
	s_mul_hi_i32 s0, s39, 0x2aaaaaab
	s_lshr_b32 s1, s0, 31
	s_ashr_i32 s6, s0, 4
	s_add_i32 s6, s6, s1
	s_mul_i32 s0, s6, 0x60
	s_sub_i32 s0, s39, s0
	v_and_b32_e32 v2, 63, v4
	v_ashrrev_i32_e32 v5, 6, v4
	s_movk_i32 s4, 0x6000
	v_lshl_or_b32 v6, s0, 6, v2
	v_mad_i64_i32 v[8:9], s[4:5], v5, s4, 0
	s_mov_b64 s[0:1], s[76:77]
	v_ashrrev_i32_e32 v7, 31, v6
	v_mad_i64_i32 v[8:9], s[4:5], s6, v24, v[8:9]
	s_waitcnt lgkmcnt(0)
	s_barrier
	v_lshl_add_u64 v[8:9], v[6:7], 2, v[8:9]
	v_mov_b32_e32 v7, 0
	v_lshl_add_u64 v[8:9], s[0:1], 0, v[8:9]
	v_lshlrev_b32_e32 v26, 2, v5
	s_mov_b64 s[0:1], 0
	v_mov_b32_e32 v14, 0
	v_mov_b32_e32 v15, v7
	v_mov_b32_e32 v12, 0
	v_mov_b32_e32 v13, v7
	v_lshl_add_u64 v[248:249], v[8:9], 0, s[0:1]
	s_mov_b64 s[98:99], 0x18000
	global_load_dword v101, v[248:249], off
	v_lshl_add_u64 v[248:249], v[248:249], 0, s[98:99]
	global_load_dword v102, v[248:249], off
	v_lshl_add_u64 v[248:249], v[248:249], 0, s[98:99]
	global_load_dword v103, v[248:249], off
	v_lshl_add_u64 v[248:249], v[248:249], 0, s[98:99]
	global_load_dword v104, v[248:249], off
	v_lshl_add_u64 v[248:249], v[248:249], 0, s[98:99]
	global_load_dword v105, v[248:249], off
	v_lshl_add_u64 v[248:249], v[248:249], 0, s[98:99]
	global_load_dword v106, v[248:249], off
	v_lshl_add_u64 v[248:249], v[248:249], 0, s[98:99]
	global_load_dword v107, v[248:249], off
	v_lshl_add_u64 v[248:249], v[248:249], 0, s[98:99]
	global_load_dword v108, v[248:249], off
	v_lshl_add_u64 v[248:249], v[248:249], 0, s[98:99]
	global_load_dword v109, v[248:249], off
	v_lshl_add_u64 v[248:249], v[248:249], 0, s[98:99]
	global_load_dword v110, v[248:249], off
	v_lshl_add_u64 v[248:249], v[248:249], 0, s[98:99]
	global_load_dword v111, v[248:249], off
	v_lshl_add_u64 v[248:249], v[248:249], 0, s[98:99]
	global_load_dword v112, v[248:249], off
	v_lshl_add_u64 v[248:249], v[248:249], 0, s[98:99]
	global_load_dword v113, v[248:249], off
	v_lshl_add_u64 v[248:249], v[248:249], 0, s[98:99]
	global_load_dword v114, v[248:249], off
	v_lshl_add_u64 v[248:249], v[248:249], 0, s[98:99]
	global_load_dword v115, v[248:249], off
	v_lshl_add_u64 v[248:249], v[248:249], 0, s[98:99]
	global_load_dword v116, v[248:249], off
	v_lshl_add_u64 v[248:249], v[248:249], 0, s[98:99]
	global_load_dword v117, v[248:249], off
	v_lshl_add_u64 v[248:249], v[248:249], 0, s[98:99]
	global_load_dword v118, v[248:249], off
	v_lshl_add_u64 v[248:249], v[248:249], 0, s[98:99]
	global_load_dword v119, v[248:249], off
	v_lshl_add_u64 v[248:249], v[248:249], 0, s[98:99]
	global_load_dword v120, v[248:249], off
	v_lshl_add_u64 v[248:249], v[248:249], 0, s[98:99]
	global_load_dword v121, v[248:249], off
	v_lshl_add_u64 v[248:249], v[248:249], 0, s[98:99]
	global_load_dword v122, v[248:249], off
	v_lshl_add_u64 v[248:249], v[248:249], 0, s[98:99]
	global_load_dword v123, v[248:249], off
	v_lshl_add_u64 v[248:249], v[248:249], 0, s[98:99]
	global_load_dword v124, v[248:249], off
	v_lshl_add_u64 v[248:249], v[248:249], 0, s[98:99]
	global_load_dword v125, v[248:249], off
	v_lshl_add_u64 v[248:249], v[248:249], 0, s[98:99]
	global_load_dword v126, v[248:249], off
	v_lshl_add_u64 v[248:249], v[248:249], 0, s[98:99]
	global_load_dword v127, v[248:249], off
	v_lshl_add_u64 v[248:249], v[248:249], 0, s[98:99]
	global_load_dword v128, v[248:249], off
	v_lshl_add_u64 v[248:249], v[248:249], 0, s[98:99]
	global_load_dword v129, v[248:249], off
	v_lshl_add_u64 v[248:249], v[248:249], 0, s[98:99]
	global_load_dword v130, v[248:249], off
	v_lshl_add_u64 v[248:249], v[248:249], 0, s[98:99]
	global_load_dword v131, v[248:249], off
	v_lshl_add_u64 v[248:249], v[248:249], 0, s[98:99]
	global_load_dword v132, v[248:249], off
.LBB0_55:
	s_waitcnt vmcnt(0)
	v_mov_b32_e32 v133, v101
	v_mov_b32_e32 v134, v102
	v_mov_b32_e32 v135, v103
	v_mov_b32_e32 v136, v104
	v_mov_b32_e32 v137, v105
	v_mov_b32_e32 v138, v106
	v_mov_b32_e32 v139, v107
	v_mov_b32_e32 v140, v108
	v_mov_b32_e32 v141, v109
	v_mov_b32_e32 v142, v110
	v_mov_b32_e32 v143, v111
	v_mov_b32_e32 v144, v112
	v_mov_b32_e32 v145, v113
	v_mov_b32_e32 v146, v114
	v_mov_b32_e32 v147, v115
	v_mov_b32_e32 v148, v116
	v_mov_b32_e32 v149, v117
	v_mov_b32_e32 v150, v118
	v_mov_b32_e32 v151, v119
	v_mov_b32_e32 v152, v120
	v_mov_b32_e32 v153, v121
	v_mov_b32_e32 v154, v122
	v_mov_b32_e32 v155, v123
	v_mov_b32_e32 v156, v124
	v_mov_b32_e32 v157, v125
	v_mov_b32_e32 v158, v126
	v_mov_b32_e32 v159, v127
	v_mov_b32_e32 v160, v128
	v_mov_b32_e32 v161, v129
	v_mov_b32_e32 v162, v130
	v_mov_b32_e32 v163, v131
	v_mov_b32_e32 v164, v132
	s_cmp_eq_u32 s0, 0x1500000
	s_cbranch_scc1 .Lmod_nopf
	v_lshl_add_u64 v[248:249], v[8:9], 0, s[0:1]
	s_mov_b64 s[98:99], 0x300000
	v_lshl_add_u64 v[248:249], v[248:249], 0, s[98:99]
	s_mov_b64 s[98:99], 0x18000
	global_load_dword v101, v[248:249], off
	v_lshl_add_u64 v[248:249], v[248:249], 0, s[98:99]
	global_load_dword v102, v[248:249], off
	v_lshl_add_u64 v[248:249], v[248:249], 0, s[98:99]
	global_load_dword v103, v[248:249], off
	v_lshl_add_u64 v[248:249], v[248:249], 0, s[98:99]
	global_load_dword v104, v[248:249], off
	v_lshl_add_u64 v[248:249], v[248:249], 0, s[98:99]
	global_load_dword v105, v[248:249], off
	v_lshl_add_u64 v[248:249], v[248:249], 0, s[98:99]
	global_load_dword v106, v[248:249], off
	v_lshl_add_u64 v[248:249], v[248:249], 0, s[98:99]
	global_load_dword v107, v[248:249], off
	v_lshl_add_u64 v[248:249], v[248:249], 0, s[98:99]
	global_load_dword v108, v[248:249], off
	v_lshl_add_u64 v[248:249], v[248:249], 0, s[98:99]
	global_load_dword v109, v[248:249], off
	v_lshl_add_u64 v[248:249], v[248:249], 0, s[98:99]
	global_load_dword v110, v[248:249], off
	v_lshl_add_u64 v[248:249], v[248:249], 0, s[98:99]
	global_load_dword v111, v[248:249], off
	v_lshl_add_u64 v[248:249], v[248:249], 0, s[98:99]
	global_load_dword v112, v[248:249], off
	v_lshl_add_u64 v[248:249], v[248:249], 0, s[98:99]
	global_load_dword v113, v[248:249], off
	v_lshl_add_u64 v[248:249], v[248:249], 0, s[98:99]
	global_load_dword v114, v[248:249], off
	v_lshl_add_u64 v[248:249], v[248:249], 0, s[98:99]
	global_load_dword v115, v[248:249], off
	v_lshl_add_u64 v[248:249], v[248:249], 0, s[98:99]
	global_load_dword v116, v[248:249], off
	v_lshl_add_u64 v[248:249], v[248:249], 0, s[98:99]
	global_load_dword v117, v[248:249], off
	v_lshl_add_u64 v[248:249], v[248:249], 0, s[98:99]
	global_load_dword v118, v[248:249], off
	v_lshl_add_u64 v[248:249], v[248:249], 0, s[98:99]
	global_load_dword v119, v[248:249], off
	v_lshl_add_u64 v[248:249], v[248:249], 0, s[98:99]
	global_load_dword v120, v[248:249], off
	v_lshl_add_u64 v[248:249], v[248:249], 0, s[98:99]
	global_load_dword v121, v[248:249], off
	v_lshl_add_u64 v[248:249], v[248:249], 0, s[98:99]
	global_load_dword v122, v[248:249], off
	v_lshl_add_u64 v[248:249], v[248:249], 0, s[98:99]
	global_load_dword v123, v[248:249], off
	v_lshl_add_u64 v[248:249], v[248:249], 0, s[98:99]
	global_load_dword v124, v[248:249], off
	v_lshl_add_u64 v[248:249], v[248:249], 0, s[98:99]
	global_load_dword v125, v[248:249], off
	v_lshl_add_u64 v[248:249], v[248:249], 0, s[98:99]
	global_load_dword v126, v[248:249], off
	v_lshl_add_u64 v[248:249], v[248:249], 0, s[98:99]
	global_load_dword v127, v[248:249], off
	v_lshl_add_u64 v[248:249], v[248:249], 0, s[98:99]
	global_load_dword v128, v[248:249], off
	v_lshl_add_u64 v[248:249], v[248:249], 0, s[98:99]
	global_load_dword v129, v[248:249], off
	v_lshl_add_u64 v[248:249], v[248:249], 0, s[98:99]
	global_load_dword v130, v[248:249], off
	v_lshl_add_u64 v[248:249], v[248:249], 0, s[98:99]
	global_load_dword v131, v[248:249], off
	v_lshl_add_u64 v[248:249], v[248:249], 0, s[98:99]
	global_load_dword v132, v[248:249], off
.Lmod_nopf:
	v_lshl_add_u64 v[10:11], v[8:9], 0, s[0:1]
	v_mov_b32_e32 v28, v133
	v_add_u32_e32 v27, 0x1000, v26
	ds_read2_b32 v[30:31], v27 offset1:4
	ds_read2_b32 v[32:33], v26 offset1:4
	ds_read2_b32 v[34:35], v26 offset0:8 offset1:12
	s_mov_b32 s4, 0x18000
	s_add_u32 s0, s0, 0x300000
	s_waitcnt lgkmcnt(2)
	v_mov_b32_e32 v37, v30
	s_waitcnt lgkmcnt(1)
	v_mov_b32_e32 v36, v32
	v_mov_b32_e32 v30, v33
	s_addc_u32 s1, s1, 0
	s_cmp_eq_u32 s0, 0x1800000
	v_pk_fma_f32 v[36:37], v[28:29], v[36:37], v[14:15] op_sel_hi:[0,1,1]
	v_add_u32_e32 v14, 0x2000, v26
	v_add_u32_e32 v15, 0x3000, v26
	ds_read2_b32 v[38:39], v14 offset1:4
	ds_read2_b32 v[40:41], v15 offset1:4
	s_waitcnt lgkmcnt(1)
	v_mov_b32_e32 v42, v38
	s_waitcnt lgkmcnt(0)
	v_mov_b32_e32 v43, v40
	v_pk_fma_f32 v[42:43], v[28:29], v[42:43], v[12:13] op_sel_hi:[0,1,1]
	v_add_u32_e32 v12, 0x4000, v26
	ds_read2_b32 v[44:45], v12 offset1:4
	v_mov_b32_e32 v40, v39
	v_mov_b32_e32 v38, v34
	s_waitcnt lgkmcnt(0)
	v_fmac_f32_e32 v7, v28, v44
	v_add_co_u32_e32 v28, vcc, s4, v10
	s_mov_b32 s4, 0x30000
	s_nop 0
	v_addc_co_u32_e32 v29, vcc, 0, v11, vcc
	v_mov_b32_e32 v28, v134
	v_pk_fma_f32 v[30:31], v[28:29], v[30:31], v[36:37] op_sel_hi:[0,1,1]
	v_pk_fma_f32 v[32:33], v[28:29], v[40:41], v[42:43] op_sel_hi:[0,1,1]
	v_fmac_f32_e32 v7, v28, v45
	v_add_co_u32_e32 v28, vcc, s4, v10
	ds_read2_b32 v[36:37], v27 offset0:8 offset1:12
	s_nop 0
	v_addc_co_u32_e32 v29, vcc, 0, v11, vcc
	v_mov_b32_e32 v28, v135
	s_mov_b32 s4, 0x48000
	s_waitcnt lgkmcnt(0)
	v_mov_b32_e32 v39, v36
	v_mov_b32_e32 v36, v35
	v_pk_fma_f32 v[30:31], v[28:29], v[38:39], v[30:31] op_sel_hi:[0,1,1]
	ds_read2_b32 v[38:39], v14 offset0:8 offset1:12
	ds_read2_b32 v[40:41], v15 offset0:8 offset1:12
	s_waitcnt lgkmcnt(1)
	v_mov_b32_e32 v42, v38
	s_waitcnt lgkmcnt(0)
	v_mov_b32_e32 v43, v40
	v_pk_fma_f32 v[32:33], v[28:29], v[42:43], v[32:33] op_sel_hi:[0,1,1]
	ds_read2_b32 v[42:43], v12 offset0:8 offset1:12
	v_mov_b32_e32 v40, v39
	s_waitcnt lgkmcnt(0)
	v_fmac_f32_e32 v7, v28, v42
	v_add_co_u32_e32 v28, vcc, s4, v10
	s_mov_b32 s4, 0x60000
	s_nop 0
	v_addc_co_u32_e32 v29, vcc, 0, v11, vcc
	v_mov_b32_e32 v28, v136
	v_pk_fma_f32 v[30:31], v[28:29], v[36:37], v[30:31] op_sel_hi:[0,1,1]
	v_pk_fma_f32 v[32:33], v[28:29], v[40:41], v[32:33] op_sel_hi:[0,1,1]
	v_fmac_f32_e32 v7, v28, v43
	v_add_co_u32_e32 v28, vcc, s4, v10
	s_mov_b32 s4, 0x78000
	s_nop 0
	v_addc_co_u32_e32 v29, vcc, 0, v11, vcc
	v_mov_b32_e32 v28, v137
	ds_read2_b32 v[34:35], v26 offset0:16 offset1:20
	ds_read2_b32 v[36:37], v27 offset0:16 offset1:20
	s_waitcnt lgkmcnt(1)
	v_mov_b32_e32 v38, v34
	s_waitcnt lgkmcnt(0)
	v_mov_b32_e32 v39, v36
	v_mov_b32_e32 v36, v35
	v_pk_fma_f32 v[30:31], v[28:29], v[38:39], v[30:31] op_sel_hi:[0,1,1]
	ds_read2_b32 v[38:39], v14 offset0:16 offset1:20
	ds_read2_b32 v[40:41], v15 offset0:16 offset1:20
	s_waitcnt lgkmcnt(1)
	v_mov_b32_e32 v42, v38
	s_waitcnt lgkmcnt(0)
	v_mov_b32_e32 v43, v40
	v_pk_fma_f32 v[32:33], v[28:29], v[42:43], v[32:33] op_sel_hi:[0,1,1]
	ds_read2_b32 v[42:43], v12 offset0:16 offset1:20
	v_mov_b32_e32 v40, v39
	s_waitcnt lgkmcnt(0)
	v_fmac_f32_e32 v7, v28, v42
	v_add_co_u32_e32 v28, vcc, s4, v10
	s_mov_b32 s4, 0x90000
	s_nop 0
	v_addc_co_u32_e32 v29, vcc, 0, v11, vcc
	v_mov_b32_e32 v28, v138
	v_pk_fma_f32 v[30:31], v[28:29], v[36:37], v[30:31] op_sel_hi:[0,1,1]
	v_pk_fma_f32 v[32:33], v[28:29], v[40:41], v[32:33] op_sel_hi:[0,1,1]
	v_fmac_f32_e32 v7, v28, v43
	v_add_co_u32_e32 v28, vcc, s4, v10
	s_mov_b32 s4, 0xa8000
	s_nop 0
	v_addc_co_u32_e32 v29, vcc, 0, v11, vcc
	v_mov_b32_e32 v28, v139
	ds_read2_b32 v[34:35], v26 offset0:24 offset1:28
	ds_read2_b32 v[36:37], v27 offset0:24 offset1:28
	s_waitcnt lgkmcnt(1)
	v_mov_b32_e32 v38, v34
	s_waitcnt lgkmcnt(0)
	v_mov_b32_e32 v39, v36
	v_mov_b32_e32 v36, v35
	v_pk_fma_f32 v[30:31], v[28:29], v[38:39], v[30:31] op_sel_hi:[0,1,1]
	ds_read2_b32 v[38:39], v14 offset0:24 offset1:28
	ds_read2_b32 v[40:41], v15 offset0:24 offset1:28
	s_waitcnt lgkmcnt(1)
	v_mov_b32_e32 v42, v38
	s_waitcnt lgkmcnt(0)
	v_mov_b32_e32 v43, v40
	v_pk_fma_f32 v[32:33], v[28:29], v[42:43], v[32:33] op_sel_hi:[0,1,1]
	ds_read2_b32 v[42:43], v12 offset0:24 offset1:28
	v_mov_b32_e32 v40, v39
	s_waitcnt lgkmcnt(0)
	v_fmac_f32_e32 v7, v28, v42
	v_add_co_u32_e32 v28, vcc, s4, v10
	s_mov_b32 s4, 0xc0000
	s_nop 0
	v_addc_co_u32_e32 v29, vcc, 0, v11, vcc
	v_mov_b32_e32 v28, v140
	v_pk_fma_f32 v[30:31], v[28:29], v[36:37], v[30:31] op_sel_hi:[0,1,1]
	v_pk_fma_f32 v[32:33], v[28:29], v[40:41], v[32:33] op_sel_hi:[0,1,1]
	v_fmac_f32_e32 v7, v28, v43
	v_add_co_u32_e32 v28, vcc, s4, v10
	s_mov_b32 s4, 0xd8000
	s_nop 0
	v_addc_co_u32_e32 v29, vcc, 0, v11, vcc
	v_mov_b32_e32 v28, v141
	ds_read2_b32 v[34:35], v26 offset0:32 offset1:36
	ds_read2_b32 v[36:37], v27 offset0:32 offset1:36
	s_waitcnt lgkmcnt(1)
	v_mov_b32_e32 v38, v34
	s_waitcnt lgkmcnt(0)
	v_mov_b32_e32 v39, v36
	v_mov_b32_e32 v36, v35
	v_pk_fma_f32 v[30:31], v[28:29], v[38:39], v[30:31] op_sel_hi:[0,1,1]
	ds_read2_b32 v[38:39], v14 offset0:32 offset1:36
	ds_read2_b32 v[40:41], v15 offset0:32 offset1:36
	s_waitcnt lgkmcnt(1)
	v_mov_b32_e32 v42, v38
	s_waitcnt lgkmcnt(0)
	v_mov_b32_e32 v43, v40
	v_pk_fma_f32 v[32:33], v[28:29], v[42:43], v[32:33] op_sel_hi:[0,1,1]
	ds_read2_b32 v[42:43], v12 offset0:32 offset1:36
	v_mov_b32_e32 v40, v39
	s_waitcnt lgkmcnt(0)
	v_fmac_f32_e32 v7, v28, v42
	v_add_co_u32_e32 v28, vcc, s4, v10
	s_mov_b32 s4, 0xf0000
	s_nop 0
	v_addc_co_u32_e32 v29, vcc, 0, v11, vcc
	v_mov_b32_e32 v28, v142
	v_pk_fma_f32 v[30:31], v[28:29], v[36:37], v[30:31] op_sel_hi:[0,1,1]
	v_pk_fma_f32 v[32:33], v[28:29], v[40:41], v[32:33] op_sel_hi:[0,1,1]
	v_fmac_f32_e32 v7, v28, v43
	v_add_co_u32_e32 v28, vcc, s4, v10
	s_mov_b32 s4, 0x108000
	s_nop 0
	v_addc_co_u32_e32 v29, vcc, 0, v11, vcc
	v_mov_b32_e32 v28, v143
	ds_read2_b32 v[34:35], v26 offset0:40 offset1:44
	ds_read2_b32 v[36:37], v27 offset0:40 offset1:44
	s_waitcnt lgkmcnt(1)
	v_mov_b32_e32 v38, v34
	s_waitcnt lgkmcnt(0)
	v_mov_b32_e32 v39, v36
	v_mov_b32_e32 v36, v35
	v_pk_fma_f32 v[30:31], v[28:29], v[38:39], v[30:31] op_sel_hi:[0,1,1]
	ds_read2_b32 v[38:39], v14 offset0:40 offset1:44
	ds_read2_b32 v[40:41], v15 offset0:40 offset1:44
	s_waitcnt lgkmcnt(1)
	v_mov_b32_e32 v42, v38
	s_waitcnt lgkmcnt(0)
	v_mov_b32_e32 v43, v40
	v_pk_fma_f32 v[32:33], v[28:29], v[42:43], v[32:33] op_sel_hi:[0,1,1]
	ds_read2_b32 v[42:43], v12 offset0:40 offset1:44
	v_mov_b32_e32 v40, v39
	s_waitcnt lgkmcnt(0)
	v_fmac_f32_e32 v7, v28, v42
	v_add_co_u32_e32 v28, vcc, s4, v10
	s_mov_b32 s4, 0x120000
	s_nop 0
	v_addc_co_u32_e32 v29, vcc, 0, v11, vcc
	v_mov_b32_e32 v28, v144
	v_pk_fma_f32 v[30:31], v[28:29], v[36:37], v[30:31] op_sel_hi:[0,1,1]
	v_pk_fma_f32 v[32:33], v[28:29], v[40:41], v[32:33] op_sel_hi:[0,1,1]
	v_fmac_f32_e32 v7, v28, v43
	v_add_co_u32_e32 v28, vcc, s4, v10
	s_mov_b32 s4, 0x138000
	s_nop 0
	v_addc_co_u32_e32 v29, vcc, 0, v11, vcc
	v_mov_b32_e32 v28, v145
	ds_read2_b32 v[34:35], v26 offset0:48 offset1:52
	ds_read2_b32 v[36:37], v27 offset0:48 offset1:52
	s_waitcnt lgkmcnt(1)
	v_mov_b32_e32 v38, v34
	s_waitcnt lgkmcnt(0)
	v_mov_b32_e32 v39, v36
	v_mov_b32_e32 v36, v35
	v_pk_fma_f32 v[30:31], v[28:29], v[38:39], v[30:31] op_sel_hi:[0,1,1]
	ds_read2_b32 v[38:39], v14 offset0:48 offset1:52
	ds_read2_b32 v[40:41], v15 offset0:48 offset1:52
	s_waitcnt lgkmcnt(1)
	v_mov_b32_e32 v42, v38
	s_waitcnt lgkmcnt(0)
	v_mov_b32_e32 v43, v40
	v_pk_fma_f32 v[32:33], v[28:29], v[42:43], v[32:33] op_sel_hi:[0,1,1]
	ds_read2_b32 v[42:43], v12 offset0:48 offset1:52
	v_mov_b32_e32 v40, v39
	s_waitcnt lgkmcnt(0)
	v_fmac_f32_e32 v7, v28, v42
	v_add_co_u32_e32 v28, vcc, s4, v10
	s_mov_b32 s4, 0x150000
	s_nop 0
	v_addc_co_u32_e32 v29, vcc, 0, v11, vcc
	v_mov_b32_e32 v28, v146
	v_pk_fma_f32 v[30:31], v[28:29], v[36:37], v[30:31] op_sel_hi:[0,1,1]
	v_pk_fma_f32 v[32:33], v[28:29], v[40:41], v[32:33] op_sel_hi:[0,1,1]
	v_fmac_f32_e32 v7, v28, v43
	v_add_co_u32_e32 v28, vcc, s4, v10
	s_mov_b32 s4, 0x168000
	s_nop 0
	v_addc_co_u32_e32 v29, vcc, 0, v11, vcc
	v_mov_b32_e32 v28, v147
	ds_read2_b32 v[34:35], v26 offset0:56 offset1:60
	ds_read2_b32 v[36:37], v27 offset0:56 offset1:60
	s_waitcnt lgkmcnt(1)
	v_mov_b32_e32 v38, v34
	s_waitcnt lgkmcnt(0)
	v_mov_b32_e32 v39, v36
	v_mov_b32_e32 v36, v35
	v_pk_fma_f32 v[30:31], v[28:29], v[38:39], v[30:31] op_sel_hi:[0,1,1]
	ds_read2_b32 v[38:39], v14 offset0:56 offset1:60
	ds_read2_b32 v[40:41], v15 offset0:56 offset1:60
	s_waitcnt lgkmcnt(1)
	v_mov_b32_e32 v42, v38
	s_waitcnt lgkmcnt(0)
	v_mov_b32_e32 v43, v40
	v_pk_fma_f32 v[32:33], v[28:29], v[42:43], v[32:33] op_sel_hi:[0,1,1]
	ds_read2_b32 v[42:43], v12 offset0:56 offset1:60
	v_mov_b32_e32 v40, v39
	s_waitcnt lgkmcnt(0)
	v_fmac_f32_e32 v7, v28, v42
	v_add_co_u32_e32 v28, vcc, s4, v10
	s_mov_b32 s4, 0x180000
	s_nop 0
	v_addc_co_u32_e32 v29, vcc, 0, v11, vcc
	v_mov_b32_e32 v28, v148
	v_pk_fma_f32 v[30:31], v[28:29], v[36:37], v[30:31] op_sel_hi:[0,1,1]
	v_pk_fma_f32 v[32:33], v[28:29], v[40:41], v[32:33] op_sel_hi:[0,1,1]
	v_fmac_f32_e32 v7, v28, v43
	v_add_co_u32_e32 v28, vcc, s4, v10
	s_mov_b32 s4, 0x198000
	s_nop 0
	v_addc_co_u32_e32 v29, vcc, 0, v11, vcc
	v_mov_b32_e32 v28, v149
	ds_read2_b32 v[34:35], v26 offset0:64 offset1:68
	ds_read2_b32 v[36:37], v27 offset0:64 offset1:68
	s_waitcnt lgkmcnt(1)
	v_mov_b32_e32 v38, v34
	s_waitcnt lgkmcnt(0)
	v_mov_b32_e32 v39, v36
	v_mov_b32_e32 v36, v35
	v_pk_fma_f32 v[30:31], v[28:29], v[38:39], v[30:31] op_sel_hi:[0,1,1]
	ds_read2_b32 v[38:39], v14 offset0:64 offset1:68
	ds_read2_b32 v[40:41], v15 offset0:64 offset1:68
	s_waitcnt lgkmcnt(1)
	v_mov_b32_e32 v42, v38
	s_waitcnt lgkmcnt(0)
	v_mov_b32_e32 v43, v40
	v_pk_fma_f32 v[32:33], v[28:29], v[42:43], v[32:33] op_sel_hi:[0,1,1]
	ds_read2_b32 v[42:43], v12 offset0:64 offset1:68
	v_mov_b32_e32 v40, v39
	s_waitcnt lgkmcnt(0)
	v_fmac_f32_e32 v7, v28, v42
	v_add_co_u32_e32 v28, vcc, s4, v10
	s_mov_b32 s4, 0x1b0000
	s_nop 0
	v_addc_co_u32_e32 v29, vcc, 0, v11, vcc
	v_mov_b32_e32 v28, v150
	v_pk_fma_f32 v[30:31], v[28:29], v[36:37], v[30:31] op_sel_hi:[0,1,1]
	v_pk_fma_f32 v[32:33], v[28:29], v[40:41], v[32:33] op_sel_hi:[0,1,1]
	v_fmac_f32_e32 v7, v28, v43
	v_add_co_u32_e32 v28, vcc, s4, v10
	s_mov_b32 s4, 0x1c8000
	s_nop 0
	v_addc_co_u32_e32 v29, vcc, 0, v11, vcc
	v_mov_b32_e32 v28, v151
	ds_read2_b32 v[34:35], v26 offset0:72 offset1:76
	ds_read2_b32 v[36:37], v27 offset0:72 offset1:76
	s_waitcnt lgkmcnt(1)
	v_mov_b32_e32 v38, v34
	s_waitcnt lgkmcnt(0)
	v_mov_b32_e32 v39, v36
	v_mov_b32_e32 v36, v35
	v_pk_fma_f32 v[30:31], v[28:29], v[38:39], v[30:31] op_sel_hi:[0,1,1]
	ds_read2_b32 v[38:39], v14 offset0:72 offset1:76
	ds_read2_b32 v[40:41], v15 offset0:72 offset1:76
	s_waitcnt lgkmcnt(1)
	v_mov_b32_e32 v42, v38
	s_waitcnt lgkmcnt(0)
	v_mov_b32_e32 v43, v40
	v_pk_fma_f32 v[32:33], v[28:29], v[42:43], v[32:33] op_sel_hi:[0,1,1]
	ds_read2_b32 v[42:43], v12 offset0:72 offset1:76
	v_mov_b32_e32 v40, v39
	s_waitcnt lgkmcnt(0)
	v_fmac_f32_e32 v7, v28, v42
	v_add_co_u32_e32 v28, vcc, s4, v10
	s_mov_b32 s4, 0x1e0000
	s_nop 0
	v_addc_co_u32_e32 v29, vcc, 0, v11, vcc
	v_mov_b32_e32 v28, v152
	v_pk_fma_f32 v[30:31], v[28:29], v[36:37], v[30:31] op_sel_hi:[0,1,1]
	v_pk_fma_f32 v[32:33], v[28:29], v[40:41], v[32:33] op_sel_hi:[0,1,1]
	v_fmac_f32_e32 v7, v28, v43
	v_add_co_u32_e32 v28, vcc, s4, v10
	s_mov_b32 s4, 0x1f8000
	s_nop 0
	v_addc_co_u32_e32 v29, vcc, 0, v11, vcc
	v_mov_b32_e32 v28, v153
	ds_read2_b32 v[34:35], v26 offset0:80 offset1:84
	ds_read2_b32 v[36:37], v27 offset0:80 offset1:84
	s_waitcnt lgkmcnt(1)
	v_mov_b32_e32 v38, v34
	s_waitcnt lgkmcnt(0)
	v_mov_b32_e32 v39, v36
	v_mov_b32_e32 v36, v35
	v_pk_fma_f32 v[30:31], v[28:29], v[38:39], v[30:31] op_sel_hi:[0,1,1]
	ds_read2_b32 v[38:39], v14 offset0:80 offset1:84
	ds_read2_b32 v[40:41], v15 offset0:80 offset1:84
	s_waitcnt lgkmcnt(1)
	v_mov_b32_e32 v42, v38
	s_waitcnt lgkmcnt(0)
	v_mov_b32_e32 v43, v40
	v_pk_fma_f32 v[32:33], v[28:29], v[42:43], v[32:33] op_sel_hi:[0,1,1]
	ds_read2_b32 v[42:43], v12 offset0:80 offset1:84
	v_mov_b32_e32 v40, v39
	s_waitcnt lgkmcnt(0)
	v_fmac_f32_e32 v7, v28, v42
	v_add_co_u32_e32 v28, vcc, s4, v10
	s_mov_b32 s4, 0x210000
	s_nop 0
	v_addc_co_u32_e32 v29, vcc, 0, v11, vcc
	v_mov_b32_e32 v28, v154
	v_pk_fma_f32 v[30:31], v[28:29], v[36:37], v[30:31] op_sel_hi:[0,1,1]
	v_pk_fma_f32 v[32:33], v[28:29], v[40:41], v[32:33] op_sel_hi:[0,1,1]
	v_fmac_f32_e32 v7, v28, v43
	v_add_co_u32_e32 v28, vcc, s4, v10
	s_mov_b32 s4, 0x228000
	s_nop 0
	v_addc_co_u32_e32 v29, vcc, 0, v11, vcc
	v_mov_b32_e32 v28, v155
	ds_read2_b32 v[34:35], v26 offset0:88 offset1:92
	ds_read2_b32 v[36:37], v27 offset0:88 offset1:92
	s_waitcnt lgkmcnt(1)
	v_mov_b32_e32 v38, v34
	s_waitcnt lgkmcnt(0)
	v_mov_b32_e32 v39, v36
	v_mov_b32_e32 v36, v35
	v_pk_fma_f32 v[30:31], v[28:29], v[38:39], v[30:31] op_sel_hi:[0,1,1]
	ds_read2_b32 v[38:39], v14 offset0:88 offset1:92
	ds_read2_b32 v[40:41], v15 offset0:88 offset1:92
	s_waitcnt lgkmcnt(1)
	v_mov_b32_e32 v42, v38
	s_waitcnt lgkmcnt(0)
	v_mov_b32_e32 v43, v40
	v_pk_fma_f32 v[32:33], v[28:29], v[42:43], v[32:33] op_sel_hi:[0,1,1]
	ds_read2_b32 v[42:43], v12 offset0:88 offset1:92
	v_mov_b32_e32 v40, v39
	s_waitcnt lgkmcnt(0)
	v_fmac_f32_e32 v7, v28, v42
	v_add_co_u32_e32 v28, vcc, s4, v10
	s_mov_b32 s4, 0x240000
	s_nop 0
	v_addc_co_u32_e32 v29, vcc, 0, v11, vcc
	v_mov_b32_e32 v28, v156
	v_pk_fma_f32 v[30:31], v[28:29], v[36:37], v[30:31] op_sel_hi:[0,1,1]
	v_pk_fma_f32 v[32:33], v[28:29], v[40:41], v[32:33] op_sel_hi:[0,1,1]
	v_fmac_f32_e32 v7, v28, v43
	v_add_co_u32_e32 v28, vcc, s4, v10
	s_mov_b32 s4, 0x258000
	s_nop 0
	v_addc_co_u32_e32 v29, vcc, 0, v11, vcc
	v_mov_b32_e32 v28, v157
	ds_read2_b32 v[34:35], v26 offset0:96 offset1:100
	ds_read2_b32 v[36:37], v27 offset0:96 offset1:100
	s_waitcnt lgkmcnt(1)
	v_mov_b32_e32 v38, v34
	s_waitcnt lgkmcnt(0)
	v_mov_b32_e32 v39, v36
	v_mov_b32_e32 v36, v35
	v_pk_fma_f32 v[30:31], v[28:29], v[38:39], v[30:31] op_sel_hi:[0,1,1]
	ds_read2_b32 v[38:39], v14 offset0:96 offset1:100
	ds_read2_b32 v[40:41], v15 offset0:96 offset1:100
	s_waitcnt lgkmcnt(1)
	v_mov_b32_e32 v42, v38
	s_waitcnt lgkmcnt(0)
	v_mov_b32_e32 v43, v40
	v_pk_fma_f32 v[32:33], v[28:29], v[42:43], v[32:33] op_sel_hi:[0,1,1]
	ds_read2_b32 v[42:43], v12 offset0:96 offset1:100
	v_mov_b32_e32 v40, v39
	s_waitcnt lgkmcnt(0)
	v_fmac_f32_e32 v7, v28, v42
	v_add_co_u32_e32 v28, vcc, s4, v10
	s_mov_b32 s4, 0x270000
	s_nop 0
	v_addc_co_u32_e32 v29, vcc, 0, v11, vcc
	v_mov_b32_e32 v28, v158
	v_pk_fma_f32 v[30:31], v[28:29], v[36:37], v[30:31] op_sel_hi:[0,1,1]
	v_pk_fma_f32 v[32:33], v[28:29], v[40:41], v[32:33] op_sel_hi:[0,1,1]
	v_fmac_f32_e32 v7, v28, v43
	v_add_co_u32_e32 v28, vcc, s4, v10
	s_mov_b32 s4, 0x288000
	s_nop 0
	v_addc_co_u32_e32 v29, vcc, 0, v11, vcc
	v_mov_b32_e32 v28, v159
	ds_read2_b32 v[34:35], v26 offset0:104 offset1:108
	ds_read2_b32 v[36:37], v27 offset0:104 offset1:108
	s_waitcnt lgkmcnt(1)
	v_mov_b32_e32 v38, v34
	s_waitcnt lgkmcnt(0)
	v_mov_b32_e32 v39, v36
	v_mov_b32_e32 v36, v35
	v_pk_fma_f32 v[30:31], v[28:29], v[38:39], v[30:31] op_sel_hi:[0,1,1]
	ds_read2_b32 v[38:39], v14 offset0:104 offset1:108
	ds_read2_b32 v[40:41], v15 offset0:104 offset1:108
	s_waitcnt lgkmcnt(1)
	v_mov_b32_e32 v42, v38
	s_waitcnt lgkmcnt(0)
	v_mov_b32_e32 v43, v40
	v_pk_fma_f32 v[32:33], v[28:29], v[42:43], v[32:33] op_sel_hi:[0,1,1]
	ds_read2_b32 v[42:43], v12 offset0:104 offset1:108
	v_mov_b32_e32 v40, v39
	s_waitcnt lgkmcnt(0)
	v_fmac_f32_e32 v7, v28, v42
	v_add_co_u32_e32 v28, vcc, s4, v10
	s_mov_b32 s4, 0x2a0000
	s_nop 0
	v_addc_co_u32_e32 v29, vcc, 0, v11, vcc
	v_mov_b32_e32 v28, v160
	v_pk_fma_f32 v[30:31], v[28:29], v[36:37], v[30:31] op_sel_hi:[0,1,1]
	v_pk_fma_f32 v[32:33], v[28:29], v[40:41], v[32:33] op_sel_hi:[0,1,1]
	v_fmac_f32_e32 v7, v28, v43
	v_add_co_u32_e32 v28, vcc, s4, v10
	s_mov_b32 s4, 0x2b8000
	s_nop 0
	v_addc_co_u32_e32 v29, vcc, 0, v11, vcc
	v_mov_b32_e32 v28, v161
	ds_read2_b32 v[34:35], v26 offset0:112 offset1:116
	ds_read2_b32 v[36:37], v27 offset0:112 offset1:116
	s_waitcnt lgkmcnt(1)
	v_mov_b32_e32 v38, v34
	s_waitcnt lgkmcnt(0)
	v_mov_b32_e32 v39, v36
	v_mov_b32_e32 v36, v35
	v_pk_fma_f32 v[30:31], v[28:29], v[38:39], v[30:31] op_sel_hi:[0,1,1]
	ds_read2_b32 v[38:39], v14 offset0:112 offset1:116
	ds_read2_b32 v[40:41], v15 offset0:112 offset1:116
	s_waitcnt lgkmcnt(1)
	v_mov_b32_e32 v42, v38
	s_waitcnt lgkmcnt(0)
	v_mov_b32_e32 v43, v40
	v_pk_fma_f32 v[32:33], v[28:29], v[42:43], v[32:33] op_sel_hi:[0,1,1]
	ds_read2_b32 v[42:43], v12 offset0:112 offset1:116
	v_mov_b32_e32 v40, v39
	s_waitcnt lgkmcnt(0)
	v_fmac_f32_e32 v7, v28, v42
	v_add_co_u32_e32 v28, vcc, s4, v10
	s_mov_b32 s4, 0x2d0000
	s_nop 0
	v_addc_co_u32_e32 v29, vcc, 0, v11, vcc
	v_mov_b32_e32 v28, v162
	v_pk_fma_f32 v[30:31], v[28:29], v[36:37], v[30:31] op_sel_hi:[0,1,1]
	v_pk_fma_f32 v[32:33], v[28:29], v[40:41], v[32:33] op_sel_hi:[0,1,1]
	v_fmac_f32_e32 v7, v28, v43
	v_add_co_u32_e32 v28, vcc, s4, v10
	s_mov_b32 s4, 0x2e8000
	s_nop 0
	v_addc_co_u32_e32 v29, vcc, 0, v11, vcc
	v_mov_b32_e32 v28, v163
	ds_read2_b32 v[34:35], v26 offset0:120 offset1:124
	ds_read2_b32 v[36:37], v27 offset0:120 offset1:124
	v_add_co_u32_e32 v10, vcc, s4, v10
	v_add_u32_e32 v26, 0x200, v26
	s_waitcnt lgkmcnt(1)
	v_mov_b32_e32 v38, v34
	s_waitcnt lgkmcnt(0)
	v_mov_b32_e32 v39, v36
	v_addc_co_u32_e32 v11, vcc, 0, v11, vcc
	v_mov_b32_e32 v36, v35
	v_pk_fma_f32 v[30:31], v[28:29], v[38:39], v[30:31] op_sel_hi:[0,1,1]
	ds_read2_b32 v[38:39], v14 offset0:120 offset1:124
	ds_read2_b32 v[40:41], v15 offset0:120 offset1:124
	v_mov_b32_e32 v10, v164
	ds_read2_b32 v[42:43], v12 offset0:120 offset1:124
	s_waitcnt lgkmcnt(2)
	v_mov_b32_e32 v14, v38
	s_waitcnt lgkmcnt(1)
	v_mov_b32_e32 v15, v40
	v_pk_fma_f32 v[32:33], v[28:29], v[14:15], v[32:33] op_sel_hi:[0,1,1]
	s_waitcnt lgkmcnt(0)
	v_fmac_f32_e32 v7, v28, v42
	v_mov_b32_e32 v40, v39
	v_pk_fma_f32 v[14:15], v[10:11], v[36:37], v[30:31] op_sel_hi:[0,1,1]
	v_pk_fma_f32 v[12:13], v[10:11], v[40:41], v[32:33] op_sel_hi:[0,1,1]
	v_fmac_f32_e32 v7, v10, v43
	s_cbranch_scc0 .LBB0_55
	s_movk_i32 s0, 0x500
	v_mul_lo_u32 v5, v5, s0
	s_movk_i32 s0, 0x140
	v_lshl_or_b32 v5, v2, 2, v5
	s_mov_b64 s[4:5], s[62:63]
	v_cmp_gt_i32_e32 vcc, s0, v4
	ds_write2st64_b32 v5, v14, v15 offset0:80 offset1:81
	ds_write2st64_b32 v5, v12, v13 offset0:82 offset1:83
	ds_write_b32 v5, v7 offset:21504
	s_waitcnt lgkmcnt(0)
	s_barrier
	s_and_saveexec_b64 s[0:1], vcc
	s_xor_b64 s[0:1], exec, s[0:1]
	s_cbranch_execz .LBB0_7
	v_max_i32_e32 v5, 64, v4
	v_sub_u32_e32 v5, v5, v4
	s_add_u32 s4, s4, 0xe280000
	s_mul_i32 s14, s6, 5
	v_add_u32_e32 v5, 0xff, v5
	s_movk_i32 s6, 0xff
	s_addc_u32 s5, s5, 0
	v_cmp_lt_u32_e32 vcc, s6, v5
	s_mov_b64 s[8:9], -1
	s_and_saveexec_b64 s[6:7], vcc
	s_cbranch_execz .LBB0_65
	v_lshrrev_b32_e32 v7, 8, v5
	v_add_u32_e32 v5, 0x100, v4
	v_add_u32_e32 v10, -1, v7
	v_cmp_lt_u32_e32 vcc, 1, v10
	v_mov_b32_e32 v11, 0
	v_mov_b64_e32 v[8:9], v[4:5]
	s_and_saveexec_b64 s[8:9], vcc
	s_cbranch_execz .LBB0_62
	v_lshrrev_b32_e32 v8, 1, v10
	v_add_u32_e32 v8, 1, v8
	v_and_b32_e32 v11, -2, v8
	v_lshlrev_b32_e32 v12, 2, v2
	v_lshl_add_u32 v13, v4, 2, v25
	s_mov_b32 s20, 0
	s_mov_b64 s[18:19], 0
	v_mov_b64_e32 v[8:9], v[4:5]
